# NA attention: redundant exec restore/save/branch triples between the 32 bias bodies removed (wave-uniform window predicate)
# speedup vs baseline: 1.2551x; 1.0023x over previous
; template <int DK, bool NA> ...
;     ...
;           float v = s[kb][i];
;           if (NA) {
;             if (win) {
;               const int kc = kb * 32 + (i & 3) + 8 * (i >> 2) + 4 * h;
;               const bool vis = (unsigned)(kc - cs) < 16u;
;               const int idx = (kr - iw + 7) * 31 + (kc - jq + 15);
;               const float bv = biasL[vis ? idx : 0];
;               v = vis ? v + bv : -1e30f;
;             }
;           }
;           s[kb][i] = v; mx = fmaxf(mx, v);
.LBB0_972:
	v_lshlrev_b32_e32 v172, 2, v132
	ds_read_b32 v173, v172 offset:37100
	ds_read_b32 v174, v172 offset:36864
	ds_read_b32 v175, v172 offset:36868
	ds_read_b32 v176, v172 offset:36872
	ds_read_b32 v177, v172 offset:36876
	ds_read_b32 v178, v172 offset:36896
	ds_read_b32 v179, v172 offset:36900
	ds_read_b32 v180, v172 offset:36904
	ds_read_b32 v181, v172 offset:36908
	ds_read_b32 v182, v172 offset:36928
	ds_read_b32 v183, v172 offset:36932
	ds_read_b32 v184, v172 offset:36936
	ds_read_b32 v185, v172 offset:36940
	ds_read_b32 v186, v172 offset:36960
	ds_read_b32 v187, v172 offset:36964
	ds_read_b32 v188, v172 offset:36968
	ds_read_b32 v189, v172 offset:36972
	ds_read_b32 v190, v172 offset:36992
	ds_read_b32 v191, v172 offset:36996
	ds_read_b32 v192, v172 offset:37000
	ds_read_b32 v193, v172 offset:37004
	ds_read_b32 v194, v172 offset:37024
	ds_read_b32 v195, v172 offset:37028
	ds_read_b32 v196, v172 offset:37032
	ds_read_b32 v197, v172 offset:37036
	ds_read_b32 v198, v172 offset:37056
	ds_read_b32 v199, v172 offset:37060
	ds_read_b32 v200, v172 offset:37064
	ds_read_b32 v201, v172 offset:37068
	ds_read_b32 v202, v172 offset:37088
	ds_read_b32 v203, v172 offset:37092
	ds_read_b32 v204, v172 offset:37096
	s_waitcnt lgkmcnt(15)
	v_add_f32_e32 v50, v50, v174
	v_cndmask_b32_e64 v50, v222, v50, s[72:73]
.LBB0_973:
	v_readlane_b32 s0, v254, 56
	v_readlane_b32 s1, v254, 57
	s_nop 1
	s_waitcnt lgkmcnt(15)
	v_add_f32_e32 v51, v51, v175
	v_cndmask_b32_e64 v51, v222, v51, s[0:1]
.LBB0_974:
	v_readlane_b32 s0, v254, 58
	v_readlane_b32 s1, v254, 59
	s_nop 1
	s_waitcnt lgkmcnt(15)
	v_add_f32_e32 v52, v52, v176
	v_cndmask_b32_e64 v52, v222, v52, s[0:1]
.LBB0_975:
	v_readlane_b32 s0, v254, 60
	v_readlane_b32 s1, v254, 61
	s_nop 1
	s_waitcnt lgkmcnt(15)
	v_add_f32_e32 v53, v53, v177
	v_cndmask_b32_e64 v53, v222, v53, s[0:1]
.LBB0_976:
	v_readlane_b32 s0, v254, 62
	v_readlane_b32 s1, v254, 63
	s_nop 1
	s_waitcnt lgkmcnt(15)
	v_add_f32_e32 v54, v54, v178
	v_cndmask_b32_e64 v54, v222, v54, s[0:1]
.LBB0_977:
	v_readlane_b32 s0, v255, 0
	v_readlane_b32 s1, v255, 1
	s_nop 1
	s_waitcnt lgkmcnt(15)
	v_add_f32_e32 v55, v55, v179
	v_cndmask_b32_e64 v55, v222, v55, s[0:1]
.LBB0_978:
	s_waitcnt lgkmcnt(15)
	v_add_f32_e32 v56, v56, v180
	v_cndmask_b32_e64 v56, v222, v56, s[16:17]
.LBB0_979:
	s_waitcnt lgkmcnt(15)
	v_add_f32_e32 v57, v57, v181
	v_cndmask_b32_e64 v57, v222, v57, s[18:19]
.LBB0_980:
	s_waitcnt lgkmcnt(15)
	v_add_f32_e32 v58, v58, v182
	v_cndmask_b32_e64 v58, v222, v58, s[20:21]
.LBB0_981:
	s_waitcnt lgkmcnt(15)
	v_add_f32_e32 v59, v59, v183
	v_cndmask_b32_e64 v59, v222, v59, s[22:23]
.LBB0_982:
	s_waitcnt lgkmcnt(15)
	v_add_f32_e32 v60, v60, v184
	v_cndmask_b32_e64 v60, v222, v60, s[24:25]
.LBB0_983:
	s_waitcnt lgkmcnt(15)
	v_add_f32_e32 v61, v61, v185
	v_cndmask_b32_e64 v61, v222, v61, s[26:27]
.LBB0_984:
	s_waitcnt lgkmcnt(15)
	v_add_f32_e32 v62, v62, v186
	v_cndmask_b32_e64 v62, v222, v62, s[28:29]
.LBB0_985:
	s_waitcnt lgkmcnt(15)
	v_add_f32_e32 v63, v63, v187
	v_cndmask_b32_e64 v63, v222, v63, s[30:31]
.LBB0_986:
	s_waitcnt lgkmcnt(15)
	v_add_f32_e32 v64, v64, v188
	v_cndmask_b32_e64 v64, v222, v64, s[34:35]
.LBB0_987:
	s_waitcnt lgkmcnt(15)
	v_add_f32_e32 v65, v65, v189
	v_cndmask_b32_e64 v65, v222, v65, s[36:37]
.LBB0_988:
	s_waitcnt lgkmcnt(14)
	v_add_f32_e32 v34, v34, v190
	v_cndmask_b32_e64 v34, v222, v34, s[38:39]
.LBB0_989:
	s_waitcnt lgkmcnt(13)
	v_add_f32_e32 v35, v35, v191
	v_cndmask_b32_e64 v35, v222, v35, s[40:41]
.LBB0_990:
	s_waitcnt lgkmcnt(12)
	v_add_f32_e32 v36, v36, v192
	v_cndmask_b32_e64 v36, v222, v36, s[42:43]
.LBB0_991:
	s_waitcnt lgkmcnt(11)
	v_add_f32_e32 v37, v37, v193
	v_cndmask_b32_e64 v37, v222, v37, s[44:45]
.LBB0_992:
	s_waitcnt lgkmcnt(10)
	v_add_f32_e32 v38, v38, v194
	v_cndmask_b32_e64 v38, v222, v38, s[46:47]
.LBB0_993:
	s_waitcnt lgkmcnt(9)
	v_add_f32_e32 v39, v39, v195
	v_cndmask_b32_e64 v39, v222, v39, s[48:49]
.LBB0_994:
	s_waitcnt lgkmcnt(8)
	v_add_f32_e32 v40, v40, v196
	v_cndmask_b32_e64 v40, v222, v40, s[50:51]
.LBB0_995:
	s_waitcnt lgkmcnt(7)
	v_add_f32_e32 v41, v41, v197
	v_cndmask_b32_e64 v41, v222, v41, s[52:53]
.LBB0_996:
	s_waitcnt lgkmcnt(6)
	v_add_f32_e32 v42, v42, v198
	v_cndmask_b32_e64 v42, v222, v42, s[54:55]
.LBB0_997:
	s_waitcnt lgkmcnt(5)
	v_add_f32_e32 v43, v43, v199
	v_cndmask_b32_e64 v43, v222, v43, s[56:57]
.LBB0_998:
	s_waitcnt lgkmcnt(4)
	v_add_f32_e32 v44, v44, v200
	v_cndmask_b32_e64 v44, v222, v44, s[58:59]
.LBB0_999:
	s_waitcnt lgkmcnt(3)
	v_add_f32_e32 v45, v45, v201
	v_cndmask_b32_e64 v45, v222, v45, s[60:61]
.LBB0_1000:
	s_waitcnt lgkmcnt(2)
	v_add_f32_e32 v46, v46, v202
	v_cndmask_b32_e64 v46, v222, v46, s[62:63]
.LBB0_1001:
	s_waitcnt lgkmcnt(1)
	v_add_f32_e32 v47, v47, v203
	v_cndmask_b32_e64 v47, v222, v47, s[64:65]
.LBB0_1002:
	s_waitcnt lgkmcnt(0)
	v_add_f32_e32 v48, v48, v204
	v_cndmask_b32_e64 v48, v222, v48, s[66:67]
	s_or_b64 exec, exec, s[2:3]
	s_and_saveexec_b64 s[2:3], vcc
	s_cbranch_execnz .LBB0_967
	s_branch .LBB0_968
